# v19 + attention: each WG processes a contiguous block of 18 items (consecutive q tiles share half of their K/V window -> L2 reuse)
# baseline (speedup 1.0000x reference)
; __device__ __forceinline__ int lbid() { int b = blockIdx.x; asm volatile("" : "+s"(b)); return b; }
; __device__ __forceinline__ AttnGeom attn_geom(int it) {
;     AttnGeom G; G.hd = it / 192; const int qt = it % 192;
;     int T, lt; if (qt < 64) { G.seq_start = (qt >> 4) * 2048; T = 2048; lt = qt & 15; } else { G.seq_start = 8192; T = 16384; lt = qt - 64; }
;     const int g = G.hd >> 3; G.dil = g == 0 ? 1 : (g == 1 ? 4 : 16); G.n_lat = T / G.dil; const int tpr = G.n_lat >> 7; G.r = lt / tpr; G.q0 = (lt % tpr) << 7; return G;
; }
; __device__ void attn_items(const Params& p, unsigned char* shm) {
;     ...
;     int it = lbid();
;     ...
;     if (it < total) ATT_LOAD(it);
.LBB0_326:
	s_or_b64 exec, exec, s[36:37]
	s_mul_i32 s4, s80, 18
	s_cmpk_lt_i32 s4, 0x1200
	s_movk_i32 s0, 0x880
	s_cselect_b64 s[40:41], -1, 0
	v_ashrrev_i32_e32 v98, 3, v130
	v_cmp_gt_i32_e64 s[36:37], s0, v130
	s_movk_i32 s0, 0x100
	v_ashrrev_i32_e32 v47, 6, v130
	v_and_b32_e32 v93, 15, v130
	v_bfe_u32 v46, v130, 4, 2
	s_and_b64 vcc, exec, s[40:41]
	v_lshlrev_b32_e32 v48, 3, v130
	v_cmp_gt_i32_e64 s[38:39], s0, v98
	s_cbranch_vccz .LBB0_338
	s_mul_hi_i32 s0, s4, 0x2aaaaaab
	s_lshr_b32 s1, s0, 31
	s_ashr_i32 s0, s0, 5
	s_add_i32 s0, s0, s1
	s_mul_i32 s1, s0, 0xc0
	s_sub_i32 s1, s4, s1
	s_lshl_b32 s2, s1, 7
	s_and_b32 s3, s2, 0xfffff800
	s_and_b32 s5, s1, 15
	s_sub_i32 s6, s1, 64
	s_and_b32 s2, s0, -8
	s_cmp_eq_u32 s2, 8
	s_cselect_b32 s2, 2, 4
	s_cmp_gt_u32 s0, 7
	s_cselect_b32 s2, s2, 0
	s_cmp_lt_i32 s1, 64
	s_cselect_b32 s1, s5, s6
	s_movk_i32 s5, 0x800
	s_cselect_b32 s5, s5, 0x4000
	s_cselect_b32 s3, s3, 0x2000
	s_cselect_b32 s7, 4, 7
	s_lshr_b32 s6, s5, s2
	s_lshr_b32 s5, s6, 7
	s_sub_i32 s7, s7, s2
	s_add_i32 s5, s5, 0x1ffffff
	s_lshr_b32 s8, s1, s7
	s_and_b32 s1, s5, s1
	s_lshl_b32 s5, s1, 7
	s_sub_i32 s7, s5, 64
	v_add_u32_e32 v16, s7, v98
	s_lshl_b32 s42, s0, 6
	s_and_b64 s[0:1], s[36:37], s[38:39]
	v_cmp_lt_i32_e32 vcc, -1, v16
	v_mov_b32_e32 v2, v1
	v_mov_b32_e32 v3, v1
	v_mov_b32_e32 v6, v1
	v_mov_b32_e32 v7, v1
	s_ashr_i32 s43, s42, 31
	s_and_b64 s[0:1], s[0:1], vcc
	v_cmp_gt_i32_e32 vcc, s6, v16
	v_mov_b32_e32 v0, v1
	v_mov_b32_e32 v4, v1
	v_mov_b32_e32 v5, v1
	v_mov_b64_e32 v[14:15], v[6:7]
	v_mov_b64_e32 v[10:11], v[2:3]
	s_add_i32 s3, s8, s3
	v_and_or_b32 v44, v48, 56, s42
	v_mov_b32_e32 v45, s43
	s_and_b64 s[8:9], s[0:1], vcc
	v_mov_b64_e32 v[12:13], v[4:5]
	v_mov_b64_e32 v[8:9], v[0:1]
	s_and_saveexec_b64 s[0:1], s[8:9]
	s_cbranch_execz .LBB0_329
	v_lshlrev_b32_e32 v0, s2, v16
	v_add_u32_e32 v0, s3, v0
	v_mad_i64_i32 v[2:3], s[8:9], v0, s95, v[44:45]
	v_readlane_b32 s8, v252, 23
	v_lshlrev_b64 v[2:3], 1, v[2:3]
	v_readlane_b32 s9, v252, 24
	s_nop 1
	v_lshl_add_u64 v[8:9], s[8:9], 0, v[2:3]
	v_readlane_b32 s8, v252, 25
	v_readlane_b32 s9, v252, 26
	s_nop 1
	v_lshl_add_u64 v[2:3], s[8:9], 0, v[2:3]
	global_load_dwordx4 v[8:11], v[8:9], off
	s_nop 0
	global_load_dwordx4 v[12:15], v[2:3], off

; __device__ void attn_items(const Params& p, unsigned char* shm) {
;     ...
;         const AttnGeom G = attn_geom(it);
; #pragma unroll
;         for (int i = 0; i < 5; ++i) { const int e = tid + 512 * i, kk = e >> 3, c8 = e & 7;
;             if (e < 2176) {
;                 if (kk < 256) *(u32x4*)(Ks + kk * 72 + c8 * 8) = kreg[i];
; #pragma unroll
;                 for (int j = 0; j < 8; ++j) Vt[(c8 * 8 + j) * 320 + (kk ^ (c8 << 3))] = (bf16_t)((vreg[i][j >> 1] >> ((j & 1) * 16)) & 0xffffu); } }
;         const bf16x8 aq0 = q0r, aq1 = q1r;
;         __syncthreads();
;         if (it + G_ < total) ATT_LOAD(it + G_);
;         asm volatile("" ::: "memory");
;         const float* bs = BT + G.hd * 132;
;         f32x4 s[9];
; #pragma unroll
;         for (int kt = 0; kt < 9; ++kt) { const bf16_t* kr = Ks + (16 * w + 16 * kt + fr) * 72 + fq * 8;
;             f32x4 a = (f32x4){0.f, 0.f, 0.f, 0.f};
;             a = __builtin_amdgcn_mfma_f32_16x16x32_bf16(aq0, *(const bf16x8*)kr, a, 0, 0, 0);
;             a = __builtin_amdgcn_mfma_f32_16x16x32_bf16(aq1, *(const bf16x8*)(kr + 32), a, 0, 0, 0); s[kt] = a; }
;         float mx[4], ls[4];
; #pragma unroll
;         for (int i = 0; i < 4; ++i) { const int qi = fq * 4 + i; float m = -3.0e38f;
; #pragma unroll
;             for (int kt = 0; kt < 9; ++kt) { const int rel = 16 * kt + fr - 64 - qi, klat = G.q0 - 64 + 16 * w + 16 * kt + fr;
;                 const bool ok = rel >= -64 && rel <= 64 && klat >= 0 && klat < G.n_lat; const int bi = min(max(rel + 64, 0), 128);
;                 const float v = ok ? s[kt][i] + bs[bi] : -1.0e30f; s[kt][i] = v; m = fmaxf(m, v); }
;             m = fmaxf(m, __shfl_xor(m, 1)); m = fmaxf(m, __shfl_xor(m, 2)); m = fmaxf(m, __shfl_xor(m, 4)); m = fmaxf(m, __shfl_xor(m, 8));
;             float sum = 0.f;
; #pragma unroll
;             for (int kt = 0; kt < 9; ++kt) { const float pv = __expf(s[kt][i] - m); s[kt][i] = pv; sum += pv; }
;             sum += __shfl_xor(sum, 1); sum += __shfl_xor(sum, 2); sum += __shfl_xor(sum, 4); sum += __shfl_xor(sum, 8);
;             mx[i] = m; ls[i] = sum; }
;         bf16_t* Pw = Ps + w * 16 * 168;
; #pragma unroll
;         for (int i = 0; i < 4; ++i) {
; #pragma unroll
;             for (int kt = 0; kt < 9; ++kt) Pw[(fq * 4 + i) * 168 + 16 * kt + fr] = f2bf(s[kt][i]);
;             Pw[(fq * 4 + i) * 168 + 144 + fr] = 0; }
;         __syncthreads();
.LBB0_338:
	v_and_b32_e32 v2, 63, v130
	s_movk_i32 s22, 0xc00
	s_andn2_b64 vcc, exec, s[40:41]
	s_cbranch_vccnz .LBB0_453
	v_and_b32_e32 v0, 48, v130
	v_and_b32_e32 v50, 64, v140
	v_add_u32_e32 v101, 0, v0
	v_xor_b32_e32 v0, 1, v140
	v_add_u32_e32 v50, 64, v50
	v_cmp_lt_i32_e32 vcc, v0, v50
	s_movk_i32 s0, 0x1500
	v_lshlrev_b32_e32 v99, 4, v47
	v_cndmask_b32_e32 v0, v140, v0, vcc
	v_lshlrev_b32_e32 v103, 2, v0
	v_xor_b32_e32 v0, 2, v140
	v_cmp_lt_i32_e32 vcc, v0, v50
	v_and_b32_e32 v92, 56, v48
	v_lshlrev_b32_e32 v51, 4, v46
	v_cndmask_b32_e32 v0, v140, v0, vcc
	v_lshlrev_b32_e32 v104, 2, v0
	v_xor_b32_e32 v0, 4, v140
	v_cmp_lt_i32_e32 vcc, v0, v50
	s_mov_b64 s[86:87], s[90:91]
	v_add_u32_e32 v61, 0x200, v130
	v_cndmask_b32_e32 v0, v140, v0, vcc
	v_lshlrev_b32_e32 v105, 2, v0
	v_xor_b32_e32 v0, 8, v140
	v_cmp_lt_i32_e32 vcc, v0, v50
	v_ashrrev_i32_e32 v110, 3, v61
	s_movk_i32 s1, 0x680
	v_cndmask_b32_e32 v0, v140, v0, vcc
	v_lshlrev_b32_e32 v106, 2, v0
	v_mul_lo_u32 v0, v47, s0
	v_readlane_b32 s0, v254, 9
	v_cmp_gt_i32_e64 s[42:43], s1, v130
	v_add_u32_e32 v63, 0x400, v130
	v_add_u32_e32 v47, s0, v0
	s_movk_i32 s0, 0x880
	v_cmp_gt_i32_e64 s[6:7], s0, v130
	s_movk_i32 s0, 0x100
	v_mul_u32_u24_e32 v0, 0x150, v93
	v_cmp_gt_i32_e64 s[8:9], s0, v98
	v_add3_u32 v107, v47, v0, v51
	v_lshlrev_b32_e32 v0, 1, v92
	v_writelane_b32 v255, s8, 10
	v_lshl_add_u64 v[94:95], s[90:91], 0, v[0:1]
	s_mov_b64 s[90:91], s[6:7]
	v_writelane_b32 v255, s9, 11
	s_and_b64 s[6:7], s[6:7], s[8:9]
	v_writelane_b32 v255, s6, 14
	v_cmp_gt_i32_e64 s[18:19], s0, v110
	v_ashrrev_i32_e32 v111, 3, v63
	v_writelane_b32 v255, s7, 15
	v_writelane_b32 v255, s18, 16
	s_and_b64 s[6:7], s[42:43], s[18:19]
	s_movk_i32 s1, 0x480
	v_writelane_b32 v255, s19, 17
	v_writelane_b32 v255, s6, 18
	v_cmp_gt_i32_e64 s[38:39], s0, v111
	v_cmp_gt_i32_e64 s[46:47], s1, v130
	v_writelane_b32 v255, s7, 19
	v_writelane_b32 v255, s38, 20
	v_add_u32_e32 v65, 0x600, v130
	s_and_b64 s[6:7], s[46:47], s[38:39]
	v_writelane_b32 v255, s39, 21
	v_ashrrev_i32_e32 v112, 3, v65
	v_writelane_b32 v255, s6, 22
	s_movk_i32 s3, 0x280
	v_cmp_gt_i32_e64 s[40:41], s0, v112
	v_writelane_b32 v255, s7, 23
	v_cmp_gt_i32_e64 s[50:51], s3, v130
	v_writelane_b32 v255, s40, 24
	v_add_u32_e32 v67, 0x800, v130
	s_and_b64 s[6:7], s[50:51], s[40:41]
	v_writelane_b32 v255, s41, 25
	v_ashrrev_i32_e32 v113, 3, v67
	s_movk_i32 s1, 0x80
	v_writelane_b32 v255, s6, 26
	v_cmp_gt_i32_e64 s[54:55], s1, v130
	v_cmp_gt_i32_e64 s[0:1], s0, v113
	v_writelane_b32 v255, s7, 27
	v_lshlrev_b32_e32 v48, 2, v46
	v_writelane_b32 v255, s0, 28
	v_sub_u32_e32 v115, v93, v48
	v_add_u32_e32 v76, 0x80, v115
	v_writelane_b32 v255, s1, 29
	s_and_b64 s[0:1], s[54:55], s[0:1]
	v_writelane_b32 v255, s0, 30
	v_or_b32_e32 v77, 2, v48
	v_sub_u32_e32 v118, v93, v77
	v_writelane_b32 v255, s1, 31
	s_movk_i32 s0, 0x81
	v_cmp_gt_u32_e64 s[6:7], s0, v115
	v_add_u32_e32 v119, 0x80, v118
	v_or_b32_e32 v108, v48, v99
	v_writelane_b32 v254, s6, 49
	v_lshl_add_u32 v50, v93, 1, v47
	v_lshlrev_b32_e32 v44, 3, v46
	v_writelane_b32 v254, s7, 50
	v_cmp_gt_u32_e64 s[6:7], s0, v76
	v_or_b32_e32 v76, 1, v48
	v_sub_u32_e32 v116, v93, v76
	v_writelane_b32 v254, s6, 37
	v_add_u32_e32 v117, 0x80, v116
	v_or_b32_e32 v48, 3, v48
	v_writelane_b32 v254, s7, 38
	v_cmp_gt_u32_e64 s[6:7], s0, v116
	v_sub_u32_e32 v120, v93, v48
	v_add_u32_e32 v121, 0x80, v120
	v_writelane_b32 v255, s6, 0
	v_add_u32_e32 v51, v44, v99
	v_mul_u32_u24_e32 v48, 0x540, v46
	v_writelane_b32 v255, s7, 1
	v_cmp_gt_u32_e64 s[6:7], s0, v117
	v_or_b32_e32 v127, 16, v93
	v_bitop3_b32 v78, v51, v127, 24 bitop3:0x78
	v_writelane_b32 v255, s6, 2
	v_or_b32_e32 v129, 32, v93
	v_bitop3_b32 v79, v51, v129, 40 bitop3:0x78
	v_writelane_b32 v255, s7, 3
	v_cmp_gt_u32_e64 s[6:7], s0, v118
	v_or_b32_e32 v132, 48, v93
	v_bitop3_b32 v80, v51, v132, 56 bitop3:0x78
	v_writelane_b32 v255, s6, 4
	v_and_b32_e32 v3, 7, v130
	v_lshlrev_b32_e32 v49, 3, v3
	v_writelane_b32 v255, s7, 5
	v_cmp_gt_u32_e64 s[6:7], s0, v119
	v_or_b32_e32 v100, v99, v93
	v_lshrrev_b32_e32 v109, 3, v2
	v_writelane_b32 v255, s6, 6
	s_movk_i32 s2, 0x90
	v_xor_b32_e32 v60, v49, v98
; __device__ void attn_items(const Params& p, unsigned char* shm) {
;     ...
;         const AttnGeom G = attn_geom(it);
; #pragma unroll
;         for (int i = 0; i < 5; ++i) { const int e = tid + 512 * i, kk = e >> 3, c8 = e & 7;
;             if (e < 2176) {
;                 if (kk < 256) *(u32x4*)(Ks + kk * 72 + c8 * 8) = kreg[i];
; #pragma unroll
;                 for (int j = 0; j < 8; ++j) Vt[(c8 * 8 + j) * 320 + (kk ^ (c8 << 3))] = (bf16_t)((vreg[i][j >> 1] >> ((j & 1) * 16)) & 0xffffu); } }
;         const bf16x8 aq0 = q0r, aq1 = q1r;
;         __syncthreads();
;         if (it + G_ < total) ATT_LOAD(it + G_);
;         asm volatile("" ::: "memory");
;         const float* bs = BT + G.hd * 132;
;         f32x4 s[9];
; #pragma unroll
;         for (int kt = 0; kt < 9; ++kt) { const bf16_t* kr = Ks + (16 * w + 16 * kt + fr) * 72 + fq * 8;
;             f32x4 a = (f32x4){0.f, 0.f, 0.f, 0.f};
;             a = __builtin_amdgcn_mfma_f32_16x16x32_bf16(aq0, *(const bf16x8*)kr, a, 0, 0, 0);
;             a = __builtin_amdgcn_mfma_f32_16x16x32_bf16(aq1, *(const bf16x8*)(kr + 32), a, 0, 0, 0); s[kt] = a; }
;         float mx[4], ls[4];
; #pragma unroll
;         for (int i = 0; i < 4; ++i) { const int qi = fq * 4 + i; float m = -3.0e38f;
; #pragma unroll
;             for (int kt = 0; kt < 9; ++kt) { const int rel = 16 * kt + fr - 64 - qi, klat = G.q0 - 64 + 16 * w + 16 * kt + fr;
;                 const bool ok = rel >= -64 && rel <= 64 && klat >= 0 && klat < G.n_lat; const int bi = min(max(rel + 64, 0), 128);
;                 const float v = ok ? s[kt][i] + bs[bi] : -1.0e30f; s[kt][i] = v; m = fmaxf(m, v); }
;             m = fmaxf(m, __shfl_xor(m, 1)); m = fmaxf(m, __shfl_xor(m, 2)); m = fmaxf(m, __shfl_xor(m, 4)); m = fmaxf(m, __shfl_xor(m, 8));
;             float sum = 0.f;
; #pragma unroll
;             for (int kt = 0; kt < 9; ++kt) { const float pv = __expf(s[kt][i] - m); s[kt][i] = pv; sum += pv; }
;             sum += __shfl_xor(sum, 1); sum += __shfl_xor(sum, 2); sum += __shfl_xor(sum, 4); sum += __shfl_xor(sum, 8);
;             mx[i] = m; ls[i] = sum; }
;         bf16_t* Pw = Ps + w * 16 * 168;
; #pragma unroll
;         for (int i = 0; i < 4; ++i) {
; #pragma unroll
;             for (int kt = 0; kt < 9; ++kt) Pw[(fq * 4 + i) * 168 + 16 * kt + fr] = f2bf(s[kt][i]);
;             Pw[(fq * 4 + i) * 168 + 144 + fr] = 0; }
;         __syncthreads();
	v_writelane_b32 v255, s7, 7
	v_cmp_gt_u32_e64 s[6:7], s0, v120
	v_cmp_gt_u32_e64 s[0:1], s0, v121
	v_xor_b32_e32 v62, v110, v49
	v_writelane_b32 v255, s6, 12
	v_xor_b32_e32 v64, v111, v49
	v_xor_b32_e32 v66, v112, v49
	v_writelane_b32 v255, s7, 13
	v_writelane_b32 v255, s0, 8
	v_xor_b32_e32 v49, v113, v49
	v_mul_lo_u32 v114, v100, s2
	v_writelane_b32 v255, s1, 9
	s_movk_i32 s0, 0x540
	v_mad_u32_u24 v122, v46, s0, v50
	s_movk_i32 s0, 0x150
	v_mad_u32_u24 v77, v76, s0, s0
	v_add_u32_e32 v124, v50, v77
	v_mov_b32_e32 v77, 0x2a0
	v_mul_u32_u24_e32 v46, 0x150, v76
	v_mad_u32_u24 v123, v76, s0, v50
	v_mad_u32_u24 v76, v76, s0, v77
	v_add_u32_e32 v125, v50, v76
	v_mad_u32_u24 v76, v93, s3, 0
	v_bitop3_b32 v77, v51, v130, 8 bitop3:0x78
	v_lshl_add_u32 v126, v77, 1, v76
	v_add_u32_e32 v77, 0x2800, v76
	v_lshl_add_u32 v128, v78, 1, v77
	v_add_u32_e32 v78, 0x5000, v76
	v_lshl_add_u32 v131, v79, 1, v78
	v_add_u32_e32 v79, 0x7800, v76
	v_lshl_add_u32 v133, v80, 1, v79
	v_add_u32_e32 v80, 32, v51
	v_bitop3_b32 v81, v80, v130, 8 bitop3:0x78
	v_lshl_add_u32 v134, v81, 1, v76
	v_bitop3_b32 v81, v80, v127, 24 bitop3:0x78
	v_lshl_add_u32 v135, v81, 1, v77
	v_bitop3_b32 v81, v80, v129, 40 bitop3:0x78
	v_bitop3_b32 v80, v80, v132, 56 bitop3:0x78
	v_lshl_add_u32 v137, v80, 1, v79
	v_add_u32_e32 v80, 64, v51
	v_lshl_add_u32 v136, v81, 1, v78
	v_bitop3_b32 v81, v80, v130, 8 bitop3:0x78
	v_lshl_add_u32 v138, v81, 1, v76
	v_bitop3_b32 v81, v80, v127, 24 bitop3:0x78
	v_lshl_add_u32 v139, v81, 1, v77
	v_bitop3_b32 v81, v80, v129, 40 bitop3:0x78
	v_bitop3_b32 v80, v80, v132, 56 bitop3:0x78
	v_lshl_add_u32 v141, v80, 1, v79
	v_add_u32_e32 v80, 0x60, v51
	v_lshl_add_u32 v140, v81, 1, v78
	v_bitop3_b32 v81, v80, v130, 8 bitop3:0x78
	v_lshl_add_u32 v142, v81, 1, v76
	v_bitop3_b32 v81, v80, v127, 24 bitop3:0x78
	v_lshl_add_u32 v143, v81, 1, v77
	v_bitop3_b32 v81, v80, v129, 40 bitop3:0x78
	v_bitop3_b32 v80, v80, v132, 56 bitop3:0x78
	v_add_u32_e32 v51, 0x80, v51
	v_lshl_add_u32 v145, v80, 1, v79
	v_bitop3_b32 v80, v51, v130, 8 bitop3:0x78
	v_lshl_add_u32 v130, v80, 1, v76
	v_bitop3_b32 v76, v51, v127, 24 bitop3:0x78
	v_lshl_add_u32 v146, v76, 1, v77
	v_bitop3_b32 v76, v51, v129, 40 bitop3:0x78
	v_bitop3_b32 v51, v51, v132, 56 bitop3:0x78
	v_or_b32_e32 v149, 8, v109
	v_lshl_add_u32 v45, v3, 4, 0
	v_add_u32_e32 v47, v47, v0
	v_mul_u32_u24_e32 v0, 0x150, v109
	v_mul_lo_u32 v2, v98, s2
	v_lshl_add_u32 v60, v60, 1, 0
	v_mul_u32_u24_e32 v3, 0x1400, v3
	v_mul_lo_u32 v61, v110, s2
	v_lshl_add_u32 v62, v62, 1, 0
	v_mul_lo_u32 v63, v111, s2
	v_lshl_add_u32 v64, v64, 1, 0
	v_mul_lo_u32 v65, v112, s2
	v_lshl_add_u32 v66, v66, 1, 0
	v_mul_lo_u32 v67, v113, s2
	v_lshl_add_u32 v49, v49, 1, 0
	v_add_u32_e32 v68, 0x900, v114
	v_add_u32_e32 v69, 0x1200, v114
	v_add_u32_e32 v70, 0x1b00, v114
	v_add_u32_e32 v71, 0x2400, v114
	v_add_u32_e32 v72, 0x2d00, v114
	v_add_u32_e32 v73, 0x3600, v114
	v_add_u32_e32 v74, 0x3f00, v114
	v_add_u32_e32 v75, 0x4800, v114
	v_lshl_add_u32 v148, v51, 1, v79
	v_mul_u32_u24_e32 v51, 0x150, v149
	v_readlane_b32 s0, v251, 10
	s_movk_i32 s23, 0xff7f
	v_subrev_u32_e32 v102, 64, v99
	v_cmp_eq_u32_e64 s[36:37], 0, v93
	v_lshl_add_u32 v144, v81, 1, v78
	v_lshl_add_u32 v147, v76, 1, v78
	v_or_b32_e32 v150, 0x50, v93
	v_or_b32_e32 v151, 0x60, v93
	v_or_b32_e32 v152, 0x70, v93
	v_or_b32_e32 v153, 0x80, v93
	s_lshl_b32 s2, s4, 7
	s_movk_i32 s3, 0x80
	v_add_u32_e32 v154, v45, v2
	v_add_u32_e32 v155, v60, v3
	v_add_u32_e32 v156, v45, v61
	v_add_u32_e32 v157, v62, v3
	v_add_u32_e32 v158, v45, v63
	v_add_u32_e32 v159, v64, v3
	v_add_u32_e32 v160, v45, v65
	v_add_u32_e32 v161, v66, v3
	v_add_u32_e32 v162, v45, v67
	v_add_u32_e32 v163, v49, v3
	v_lshlrev_b32_e32 v96, 1, v44
	v_add_u32_e32 v164, v101, v68
	v_add_u32_e32 v165, v101, v69
	v_add_u32_e32 v166, v101, v70
	v_add_u32_e32 v167, v101, v71
	v_add_u32_e32 v168, v101, v72
	v_add_u32_e32 v169, v101, v73
	v_add_u32_e32 v170, v101, v74
	v_add_u32_e32 v171, v101, v75
	v_add_u32_e32 v172, v50, v48
	v_add_u32_e32 v173, v47, v0
	v_add_u32_e32 v174, v47, v51
	v_add_u32_e32 v175, v50, v46
	v_readlane_b32 s1, v251, 11
	s_branch .LBB0_341

; __device__ void attn_items(const Params& p, unsigned char* shm) {
;     ...
;     for (; it < total; it += G_) {
;     ...
;         if (it + G_ < total) ATT_LOAD(it + G_);
.LBB0_361:
	s_or_b64 exec, exec, s[0:1]
	s_add_i32 s15, s4, 1
	s_mul_i32 s0, s80, 18
	s_add_i32 s0, s0, 17
	s_cmp_gt_i32 s15, s0
	s_cselect_b64 s[40:41], -1, 0
	s_waitcnt vmcnt(1)
	v_mov_b64_e32 v[44:45], v[56:57]
	s_waitcnt vmcnt(0)
	v_mov_b64_e32 v[48:49], v[52:53]
	s_and_b64 vcc, exec, s[40:41]
	v_mov_b64_e32 v[46:47], v[58:59]
	v_mov_b64_e32 v[50:51], v[54:55]
	s_waitcnt lgkmcnt(0)
	s_barrier
	v_readlane_b32 s1, v251, 11
	s_cbranch_vccnz .LBB0_373
	s_mul_hi_i32 s0, s15, 0x2aaaaaab
	s_lshr_b32 s1, s0, 31
	s_ashr_i32 s0, s0, 5
	s_add_i32 s0, s0, s1
	s_mul_i32 s1, s0, 0xffffff40
	s_mul_i32 s5, s0, 0xffffa000
	s_add_i32 s6, s3, s2
	s_add_i32 s1, s15, s1
	s_add_i32 s6, s6, s5
	s_and_b32 s6, s6, 0xfffff800
	s_and_b32 s7, s1, 15
	s_sub_i32 s8, s1, 64
	s_and_b32 s5, s0, -8
	s_cmp_eq_u32 s5, 8
	s_cselect_b32 s5, 2, 4
	s_cmp_gt_u32 s0, 7
	s_cselect_b32 s5, s5, 0
	s_cmp_lt_i32 s1, 64
	s_cselect_b32 s1, s7, s8
	s_movk_i32 s7, 0x800
	s_cselect_b32 s7, s7, 0x4000
	s_cselect_b32 s10, s6, 0x2000
	s_cselect_b32 s6, 4, 7
	s_lshr_b32 s8, s7, s5
	s_lshr_b32 s7, s8, 7
	s_sub_i32 s6, s6, s5
	s_add_i32 s7, s7, -1
	s_lshr_b32 s17, s1, s6
	s_and_b32 s1, s7, s1
	s_lshl_b32 s6, s1, 7
	s_sub_i32 s9, s6, 64
	s_lshl_b32 s38, s0, 6
	v_add_u32_e32 v16, s9, v98
	v_readlane_b32 s0, v255, 14
	v_cmp_lt_i32_e32 vcc, -1, v16
	v_readlane_b32 s1, v255, 15
	v_mov_b32_e32 v2, v1
	v_mov_b32_e32 v3, v1
	v_mov_b32_e32 v6, v1
	v_mov_b32_e32 v7, v1
	s_ashr_i32 s39, s38, 31
	s_and_b64 s[0:1], s[0:1], vcc
	v_cmp_gt_i32_e32 vcc, s8, v16
	v_mov_b32_e32 v0, v1
	v_mov_b32_e32 v4, v1
	v_mov_b32_e32 v5, v1
	v_mov_b64_e32 v[14:15], v[6:7]
	v_mov_b64_e32 v[10:11], v[2:3]
	s_add_i32 s7, s17, s10
	v_mov_b32_e32 v45, s39
	v_or_b32_e32 v44, s38, v92
	s_and_b64 s[18:19], s[0:1], vcc
	v_mov_b64_e32 v[12:13], v[4:5]
	v_mov_b64_e32 v[8:9], v[0:1]
	s_and_saveexec_b64 s[0:1], s[18:19]
	s_cbranch_execz .LBB0_364
	v_lshlrev_b32_e32 v0, s5, v16
	v_add_u32_e32 v0, s7, v0
	v_mad_i64_i32 v[2:3], s[18:19], v0, s95, v[44:45]
	v_readlane_b32 s18, v252, 23
	v_lshlrev_b64 v[2:3], 1, v[2:3]
	v_readlane_b32 s19, v252, 24
	s_nop 1
	v_lshl_add_u64 v[8:9], s[18:19], 0, v[2:3]
	v_readlane_b32 s18, v252, 25
	v_readlane_b32 s19, v252, 26
	s_nop 1
	v_lshl_add_u64 v[2:3], s[18:19], 0, v[2:3]
	global_load_dwordx4 v[8:11], v[8:9], off
	s_nop 0
	global_load_dwordx4 v[12:15], v[2:3], off
